# K-loop heads of all ten GEMM phases aligned to 64 bytes (.p2align 6)
# speedup vs baseline: 1.0082x; 1.0002x over previous
;     ...
;         const bool has_next = S.next(ui + 1, nxt);
;         const bool nrev = ZIGZAG && (((ui + 1) & 1) != 0);
;         const ptrdiff_t nk = has_next ? (nrev ? -kfwd : kfwd) : ck, noff = (has_next && nrev) ? kspan : 0;
;         const char* nA = has_next ? (const char*)g.A + (size_t)nxt.pm * tstep + noff : cA; const char* nB = has_next ? (const char*)g.Bt + (size_t)nxt.pn * tstep + noff : cB;
;         for (int t = 0; t < nt; t += 2) {
;             const bool last = (t == nt - 2);
;             const char* a1 = cA + (ptrdiff_t)(t + 1) * ck;
;             const char* a2 = last ? nA : cA + (ptrdiff_t)(t + 2) * ck; const char* b2 = last ? nB : cB + (ptrdiff_t)(t + 2) * ck;
;             const ptrdiff_t k3 = last ? nk : ck;
;             const char* a3 = a2 + k3; const char* b3 = b2 + k3;
;     ...
;         for (int a = 0; a < 2; ++a)
; #pragma unroll
;             for (int b = 0; b < 2; ++b)
; #pragma unroll
;                 for (int m = 0; m < 4; ++m)
; #pragma unroll
;                     for (int n = 0; n < 2; ++n) acc[a][b][m][n] = (f32x4){0.f, 0.f, 0.f, 0.f};
;         cur = nxt; cA = nA; cB = nB; ck = nk; ++ui;
.LBB0_243:
	s_ashr_i32 s21, s20, 31
	s_lshl_b64 s[24:25], s[20:21], 19
	s_add_u32 s24, s34, s24
	s_addc_u32 s25, s35, s25
	s_and_b64 s[26:27], s[0:1], exec
	s_cselect_b32 s21, s25, s41
	s_cselect_b32 s37, s24, s40
	s_ashr_i32 s23, s22, 31
	s_lshl_b64 s[26:27], s[22:23], 19
	s_add_u32 s26, s28, s26
	s_addc_u32 s27, s29, s27
	s_and_b64 s[48:49], s[0:1], exec
	s_cselect_b32 s23, s27, s45
	s_cselect_b32 s67, s26, s44
	s_add_u32 s40, s40, 0x40080
	s_addc_u32 s41, s41, 0
	s_add_u32 s68, s44, 0x100
	v_mov_b32_e32 v0, 0
	s_addc_u32 s69, s45, 0
	s_mov_b32 s70, -2
	v_mov_b32_e32 v1, v0
	v_mov_b32_e32 v2, v0
	v_mov_b32_e32 v3, v0
	v_mov_b32_e32 v4, v0
	v_mov_b32_e32 v5, v0
	v_mov_b32_e32 v6, v0
	v_mov_b32_e32 v7, v0
	v_mov_b32_e32 v16, v0
	v_mov_b32_e32 v17, v0
	v_mov_b32_e32 v18, v0
	v_mov_b32_e32 v19, v0
	v_mov_b32_e32 v20, v0
	v_mov_b32_e32 v21, v0
	v_mov_b32_e32 v22, v0
	v_mov_b32_e32 v23, v0
	v_mov_b32_e32 v32, v0
	v_mov_b32_e32 v33, v0
	v_mov_b32_e32 v34, v0
	v_mov_b32_e32 v35, v0
	v_mov_b32_e32 v36, v0
	v_mov_b32_e32 v37, v0
	v_mov_b32_e32 v38, v0
	v_mov_b32_e32 v39, v0
	v_mov_b32_e32 v48, v0
	v_mov_b32_e32 v49, v0
	v_mov_b32_e32 v50, v0
	v_mov_b32_e32 v51, v0
	v_mov_b32_e32 v52, v0
	v_mov_b32_e32 v53, v0
	v_mov_b32_e32 v54, v0
	v_mov_b32_e32 v55, v0
	v_mov_b32_e32 v8, v0
	v_mov_b32_e32 v9, v0
	v_mov_b32_e32 v10, v0
	v_mov_b32_e32 v11, v0
	v_mov_b32_e32 v12, v0
	v_mov_b32_e32 v13, v0
	v_mov_b32_e32 v14, v0
	v_mov_b32_e32 v15, v0
	v_mov_b32_e32 v24, v0
	v_mov_b32_e32 v25, v0
	v_mov_b32_e32 v26, v0
	v_mov_b32_e32 v27, v0
	v_mov_b32_e32 v28, v0
	v_mov_b32_e32 v29, v0
	v_mov_b32_e32 v30, v0
	v_mov_b32_e32 v31, v0
	v_mov_b32_e32 v40, v0
	v_mov_b32_e32 v41, v0
	v_mov_b32_e32 v42, v0
	v_mov_b32_e32 v43, v0
	v_mov_b32_e32 v44, v0
	v_mov_b32_e32 v45, v0
	v_mov_b32_e32 v46, v0
	v_mov_b32_e32 v47, v0
	v_mov_b32_e32 v56, v0
	v_mov_b32_e32 v57, v0
	v_mov_b32_e32 v58, v0
	v_mov_b32_e32 v59, v0
	v_mov_b32_e32 v60, v0
	v_mov_b32_e32 v61, v0
	v_mov_b32_e32 v62, v0
	v_mov_b32_e32 v63, v0
	v_mov_b32_e32 v64, v0
	v_mov_b32_e32 v65, v0
	v_mov_b32_e32 v66, v0
	v_mov_b32_e32 v67, v0
	v_mov_b32_e32 v68, v0
	v_mov_b32_e32 v69, v0
	v_mov_b32_e32 v70, v0
	v_mov_b32_e32 v71, v0
	v_mov_b32_e32 v80, v0
	v_mov_b32_e32 v81, v0
	v_mov_b32_e32 v82, v0
	v_mov_b32_e32 v83, v0
	v_mov_b32_e32 v84, v0
	v_mov_b32_e32 v85, v0
	v_mov_b32_e32 v86, v0
	v_mov_b32_e32 v87, v0
	v_mov_b32_e32 v96, v0
	v_mov_b32_e32 v97, v0
	v_mov_b32_e32 v98, v0
	v_mov_b32_e32 v99, v0
	v_mov_b32_e32 v100, v0
	v_mov_b32_e32 v101, v0
	v_mov_b32_e32 v102, v0
	v_mov_b32_e32 v103, v0
	v_mov_b32_e32 v112, v0
	v_mov_b32_e32 v113, v0
	v_mov_b32_e32 v114, v0
	v_mov_b32_e32 v115, v0
	v_mov_b32_e32 v116, v0
	v_mov_b32_e32 v117, v0
	v_mov_b32_e32 v118, v0
	v_mov_b32_e32 v119, v0
	v_mov_b32_e32 v72, v0
	v_mov_b32_e32 v73, v0
	v_mov_b32_e32 v74, v0
	v_mov_b32_e32 v75, v0
	v_mov_b32_e32 v76, v0
	v_mov_b32_e32 v77, v0
	v_mov_b32_e32 v78, v0
	v_mov_b32_e32 v79, v0
	v_mov_b32_e32 v88, v0
	v_mov_b32_e32 v89, v0
	v_mov_b32_e32 v90, v0
	v_mov_b32_e32 v91, v0
	v_mov_b32_e32 v92, v0
	v_mov_b32_e32 v93, v0
	v_mov_b32_e32 v94, v0
	v_mov_b32_e32 v95, v0
	v_mov_b32_e32 v104, v0
	v_mov_b32_e32 v105, v0
	v_mov_b32_e32 v106, v0
	v_mov_b32_e32 v107, v0
	v_mov_b32_e32 v108, v0
	v_mov_b32_e32 v109, v0
	v_mov_b32_e32 v110, v0
	v_mov_b32_e32 v111, v0
	v_mov_b32_e32 v120, v0
	v_mov_b32_e32 v121, v0
	v_mov_b32_e32 v122, v0
	v_mov_b32_e32 v123, v0
	v_mov_b32_e32 v124, v0
	v_mov_b32_e32 v125, v0
	v_mov_b32_e32 v126, v0
	v_mov_b32_e32 v127, v0
	.p2align 6

;     ...
;             const char* a1 = cA + (ptrdiff_t)(t + 1) * ck;
;             const char* a2 = last ? nA : cA + (ptrdiff_t)(t + 2) * ck; const char* b2 = last ? nB : cB + (ptrdiff_t)(t + 2) * ck;
;             const ptrdiff_t k3 = last ? nk : ck;
;             const char* a3 = a2 + k3; const char* b3 = b2 + k3;
;     ...
;         for (int a = 0; a < 2; ++a)
; #pragma unroll
;             for (int b = 0; b < 2; ++b)
; #pragma unroll
;                 for (int m = 0; m < 4; ++m)
; #pragma unroll
;                     for (int n = 0; n < 2; ++n) acc[a][b][m][n] = (f32x4){0.f, 0.f, 0.f, 0.f};
;         cur = nxt; cA = nA; cB = nB; ck = nk; ++ui;
.LBB0_328:
	s_add_u32 s40, s40, 0xb0080
	s_addc_u32 s41, s41, 0
	s_add_u32 s63, s44, 0x100
	v_mov_b32_e32 v0, 0
	s_addc_u32 s66, s45, 0
	s_mov_b32 s67, -2
	v_mov_b32_e32 v1, v0
	v_mov_b32_e32 v2, v0
	v_mov_b32_e32 v3, v0
	v_mov_b32_e32 v4, v0
	v_mov_b32_e32 v5, v0
	v_mov_b32_e32 v6, v0
	v_mov_b32_e32 v7, v0
	v_mov_b32_e32 v16, v0
	v_mov_b32_e32 v17, v0
	v_mov_b32_e32 v18, v0
	v_mov_b32_e32 v19, v0
	v_mov_b32_e32 v20, v0
	v_mov_b32_e32 v21, v0
	v_mov_b32_e32 v22, v0
	v_mov_b32_e32 v23, v0
	v_mov_b32_e32 v32, v0
	v_mov_b32_e32 v33, v0
	v_mov_b32_e32 v34, v0
	v_mov_b32_e32 v35, v0
	v_mov_b32_e32 v36, v0
	v_mov_b32_e32 v37, v0
	v_mov_b32_e32 v38, v0
	v_mov_b32_e32 v39, v0
	v_mov_b32_e32 v48, v0
	v_mov_b32_e32 v49, v0
	v_mov_b32_e32 v50, v0
	v_mov_b32_e32 v51, v0
	v_mov_b32_e32 v52, v0
	v_mov_b32_e32 v53, v0
	v_mov_b32_e32 v54, v0
	v_mov_b32_e32 v55, v0
	v_mov_b32_e32 v8, v0
	v_mov_b32_e32 v9, v0
	v_mov_b32_e32 v10, v0
	v_mov_b32_e32 v11, v0
	v_mov_b32_e32 v12, v0
	v_mov_b32_e32 v13, v0
	v_mov_b32_e32 v14, v0
	v_mov_b32_e32 v15, v0
	v_mov_b32_e32 v24, v0
	v_mov_b32_e32 v25, v0
	v_mov_b32_e32 v26, v0
	v_mov_b32_e32 v27, v0
	v_mov_b32_e32 v28, v0
	v_mov_b32_e32 v29, v0
	v_mov_b32_e32 v30, v0
	v_mov_b32_e32 v31, v0
	v_mov_b32_e32 v40, v0
	v_mov_b32_e32 v41, v0
	v_mov_b32_e32 v42, v0
	v_mov_b32_e32 v43, v0
	v_mov_b32_e32 v44, v0
	v_mov_b32_e32 v45, v0
	v_mov_b32_e32 v46, v0
	v_mov_b32_e32 v47, v0
	v_mov_b32_e32 v56, v0
	v_mov_b32_e32 v57, v0
	v_mov_b32_e32 v58, v0
	v_mov_b32_e32 v59, v0
	v_mov_b32_e32 v60, v0
	v_mov_b32_e32 v61, v0
	v_mov_b32_e32 v62, v0
	v_mov_b32_e32 v63, v0
	v_mov_b32_e32 v64, v0
	v_mov_b32_e32 v65, v0
	v_mov_b32_e32 v66, v0
	v_mov_b32_e32 v67, v0
	v_mov_b32_e32 v68, v0
	v_mov_b32_e32 v69, v0
	v_mov_b32_e32 v70, v0
	v_mov_b32_e32 v71, v0
	v_mov_b32_e32 v80, v0
	v_mov_b32_e32 v81, v0
	v_mov_b32_e32 v82, v0
	v_mov_b32_e32 v83, v0
	v_mov_b32_e32 v84, v0
	v_mov_b32_e32 v85, v0
	v_mov_b32_e32 v86, v0
	v_mov_b32_e32 v87, v0
	v_mov_b32_e32 v96, v0
	v_mov_b32_e32 v97, v0
	v_mov_b32_e32 v98, v0
	v_mov_b32_e32 v99, v0
	v_mov_b32_e32 v100, v0
	v_mov_b32_e32 v101, v0
	v_mov_b32_e32 v102, v0
	v_mov_b32_e32 v103, v0
	v_mov_b32_e32 v112, v0
	v_mov_b32_e32 v113, v0
	v_mov_b32_e32 v114, v0
	v_mov_b32_e32 v115, v0
	v_mov_b32_e32 v116, v0
	v_mov_b32_e32 v117, v0
	v_mov_b32_e32 v118, v0
	v_mov_b32_e32 v119, v0
	v_mov_b32_e32 v72, v0
	v_mov_b32_e32 v73, v0
	v_mov_b32_e32 v74, v0
	v_mov_b32_e32 v75, v0
	v_mov_b32_e32 v76, v0
	v_mov_b32_e32 v77, v0
	v_mov_b32_e32 v78, v0
	v_mov_b32_e32 v79, v0
	v_mov_b32_e32 v88, v0
	v_mov_b32_e32 v89, v0
	v_mov_b32_e32 v90, v0
	v_mov_b32_e32 v91, v0
	v_mov_b32_e32 v92, v0
	v_mov_b32_e32 v93, v0
	v_mov_b32_e32 v94, v0
	v_mov_b32_e32 v95, v0
	v_mov_b32_e32 v104, v0
	v_mov_b32_e32 v105, v0
	v_mov_b32_e32 v106, v0
	v_mov_b32_e32 v107, v0
	v_mov_b32_e32 v108, v0
	v_mov_b32_e32 v109, v0
	v_mov_b32_e32 v110, v0
	v_mov_b32_e32 v111, v0
	v_mov_b32_e32 v120, v0
	v_mov_b32_e32 v121, v0
	v_mov_b32_e32 v122, v0
	v_mov_b32_e32 v123, v0
	v_mov_b32_e32 v124, v0
	v_mov_b32_e32 v125, v0
	v_mov_b32_e32 v126, v0
	v_mov_b32_e32 v127, v0
	.p2align 6

;     ...
;         const bool has_next = S.next(ui + 1, nxt);
;         const bool nrev = ZIGZAG && (((ui + 1) & 1) != 0);
;         const ptrdiff_t nk = has_next ? (nrev ? -kfwd : kfwd) : ck, noff = (has_next && nrev) ? kspan : 0;
;         const char* nA = has_next ? (const char*)g.A + (size_t)nxt.pm * tstep + noff : cA; const char* nB = has_next ? (const char*)g.Bt + (size_t)nxt.pn * tstep + noff : cB;
;         for (int t = 0; t < nt; t += 2) {
;             const bool last = (t == nt - 2);
;             const char* a1 = cA + (ptrdiff_t)(t + 1) * ck;
;             const char* a2 = last ? nA : cA + (ptrdiff_t)(t + 2) * ck; const char* b2 = last ? nB : cB + (ptrdiff_t)(t + 2) * ck;
;             const ptrdiff_t k3 = last ? nk : ck;
;             const char* a3 = a2 + k3; const char* b3 = b2 + k3;
;     ...
;         for (int a = 0; a < 2; ++a)
; #pragma unroll
;             for (int b = 0; b < 2; ++b)
; #pragma unroll
;                 for (int m = 0; m < 4; ++m)
; #pragma unroll
;                     for (int n = 0; n < 2; ++n) acc[a][b][m][n] = (f32x4){0.f, 0.f, 0.f, 0.f};
;         cur = nxt; cA = nA; cB = nB; ck = nk; ++ui;
.LBB0_515:
	s_ashr_i32 s27, s26, 31
	s_lshl_b64 s[40:41], s[26:27], 19
	s_add_u32 s40, s34, s40
	s_addc_u32 s41, s35, s41
	s_and_b64 s[44:45], s[0:1], exec
	s_cselect_b32 s5, s41, s49
	s_cselect_b32 s7, s40, s48
	s_ashr_i32 s37, s36, 31
	s_lshl_b64 s[44:45], s[36:37], 19
	s_add_u32 s44, s10, s44
	s_addc_u32 s45, s11, s45
	s_and_b64 s[52:53], s[0:1], exec
	s_cselect_b32 s27, s45, s51
	s_cselect_b32 s37, s44, s50
	s_add_u32 s48, s48, 0x40080
	s_addc_u32 s49, s49, 0
	s_add_u32 s66, s50, 0x100
	v_mov_b32_e32 v0, 0
	s_addc_u32 s67, s51, 0
	s_mov_b32 s68, -2
	v_mov_b32_e32 v1, v0
	v_mov_b32_e32 v2, v0
	v_mov_b32_e32 v3, v0
	v_mov_b32_e32 v4, v0
	v_mov_b32_e32 v5, v0
	v_mov_b32_e32 v6, v0
	v_mov_b32_e32 v7, v0
	v_mov_b32_e32 v16, v0
	v_mov_b32_e32 v17, v0
	v_mov_b32_e32 v18, v0
	v_mov_b32_e32 v19, v0
	v_mov_b32_e32 v20, v0
	v_mov_b32_e32 v21, v0
	v_mov_b32_e32 v22, v0
	v_mov_b32_e32 v23, v0
	v_mov_b32_e32 v32, v0
	v_mov_b32_e32 v33, v0
	v_mov_b32_e32 v34, v0
	v_mov_b32_e32 v35, v0
	v_mov_b32_e32 v36, v0
	v_mov_b32_e32 v37, v0
	v_mov_b32_e32 v38, v0
	v_mov_b32_e32 v39, v0
	v_mov_b32_e32 v48, v0
	v_mov_b32_e32 v49, v0
	v_mov_b32_e32 v50, v0
	v_mov_b32_e32 v51, v0
	v_mov_b32_e32 v52, v0
	v_mov_b32_e32 v53, v0
	v_mov_b32_e32 v54, v0
	v_mov_b32_e32 v55, v0
	v_mov_b32_e32 v8, v0
	v_mov_b32_e32 v9, v0
	v_mov_b32_e32 v10, v0
	v_mov_b32_e32 v11, v0
	v_mov_b32_e32 v12, v0
	v_mov_b32_e32 v13, v0
	v_mov_b32_e32 v14, v0
	v_mov_b32_e32 v15, v0
	v_mov_b32_e32 v24, v0
	v_mov_b32_e32 v25, v0
	v_mov_b32_e32 v26, v0
	v_mov_b32_e32 v27, v0
	v_mov_b32_e32 v28, v0
	v_mov_b32_e32 v29, v0
	v_mov_b32_e32 v30, v0
	v_mov_b32_e32 v31, v0
	v_mov_b32_e32 v40, v0
	v_mov_b32_e32 v41, v0
	v_mov_b32_e32 v42, v0
	v_mov_b32_e32 v43, v0
	v_mov_b32_e32 v44, v0
	v_mov_b32_e32 v45, v0
	v_mov_b32_e32 v46, v0
	v_mov_b32_e32 v47, v0
	v_mov_b32_e32 v56, v0
	v_mov_b32_e32 v57, v0
	v_mov_b32_e32 v58, v0
	v_mov_b32_e32 v59, v0
	v_mov_b32_e32 v60, v0
	v_mov_b32_e32 v61, v0
	v_mov_b32_e32 v62, v0
	v_mov_b32_e32 v63, v0
	v_mov_b32_e32 v64, v0
	v_mov_b32_e32 v65, v0
	v_mov_b32_e32 v66, v0
	v_mov_b32_e32 v67, v0
	v_mov_b32_e32 v68, v0
	v_mov_b32_e32 v69, v0
	v_mov_b32_e32 v70, v0
	v_mov_b32_e32 v71, v0
	v_mov_b32_e32 v80, v0
	v_mov_b32_e32 v81, v0
	v_mov_b32_e32 v82, v0
	v_mov_b32_e32 v83, v0
	v_mov_b32_e32 v84, v0
	v_mov_b32_e32 v85, v0
	v_mov_b32_e32 v86, v0
	v_mov_b32_e32 v87, v0
	v_mov_b32_e32 v96, v0
	v_mov_b32_e32 v97, v0
	v_mov_b32_e32 v98, v0
	v_mov_b32_e32 v99, v0
	v_mov_b32_e32 v100, v0
	v_mov_b32_e32 v101, v0
	v_mov_b32_e32 v102, v0
	v_mov_b32_e32 v103, v0
	v_mov_b32_e32 v112, v0
	v_mov_b32_e32 v113, v0
	v_mov_b32_e32 v114, v0
	v_mov_b32_e32 v115, v0
	v_mov_b32_e32 v116, v0
	v_mov_b32_e32 v117, v0
	v_mov_b32_e32 v118, v0
	v_mov_b32_e32 v119, v0
	v_mov_b32_e32 v72, v0
	v_mov_b32_e32 v73, v0
	v_mov_b32_e32 v74, v0
	v_mov_b32_e32 v75, v0
	v_mov_b32_e32 v76, v0
	v_mov_b32_e32 v77, v0
	v_mov_b32_e32 v78, v0
	v_mov_b32_e32 v79, v0
	v_mov_b32_e32 v88, v0
	v_mov_b32_e32 v89, v0
	v_mov_b32_e32 v90, v0
	v_mov_b32_e32 v91, v0
	v_mov_b32_e32 v92, v0
	v_mov_b32_e32 v93, v0
	v_mov_b32_e32 v94, v0
	v_mov_b32_e32 v95, v0
	v_mov_b32_e32 v104, v0
	v_mov_b32_e32 v105, v0
	v_mov_b32_e32 v106, v0
	v_mov_b32_e32 v107, v0
	v_mov_b32_e32 v108, v0
	v_mov_b32_e32 v109, v0
	v_mov_b32_e32 v110, v0
	v_mov_b32_e32 v111, v0
	v_mov_b32_e32 v120, v0
	v_mov_b32_e32 v121, v0
	v_mov_b32_e32 v122, v0
	v_mov_b32_e32 v123, v0
	v_mov_b32_e32 v124, v0
	v_mov_b32_e32 v125, v0
	v_mov_b32_e32 v126, v0
	v_mov_b32_e32 v127, v0
	.p2align 6

;     ...
;         const bool has_next = S.next(ui + 1, nxt);
;         const bool nrev = ZIGZAG && (((ui + 1) & 1) != 0);
;         const ptrdiff_t nk = has_next ? (nrev ? -kfwd : kfwd) : ck, noff = (has_next && nrev) ? kspan : 0;
;         const char* nA = has_next ? (const char*)g.A + (size_t)nxt.pm * tstep + noff : cA; const char* nB = has_next ? (const char*)g.Bt + (size_t)nxt.pn * tstep + noff : cB;
;         for (int t = 0; t < nt; t += 2) {
;             const bool last = (t == nt - 2);
;             const char* a1 = cA + (ptrdiff_t)(t + 1) * ck;
;             const char* a2 = last ? nA : cA + (ptrdiff_t)(t + 2) * ck; const char* b2 = last ? nB : cB + (ptrdiff_t)(t + 2) * ck;
;             const ptrdiff_t k3 = last ? nk : ck;
;             const char* a3 = a2 + k3; const char* b3 = b2 + k3;
;     ...
;         for (int a = 0; a < 2; ++a)
; #pragma unroll
;             for (int b = 0; b < 2; ++b)
; #pragma unroll
;                 for (int m = 0; m < 4; ++m)
; #pragma unroll
;                     for (int n = 0; n < 2; ++n) acc[a][b][m][n] = (f32x4){0.f, 0.f, 0.f, 0.f};
;         cur = nxt; cA = nA; cB = nB; ck = nk; ++ui;
.LBB0_786:
	s_ashr_i32 s25, s24, 31
	s_lshl_b64 s[38:39], s[24:25], 19
	s_add_u32 s38, s16, s38
	s_addc_u32 s39, s17, s39
	s_and_b64 s[40:41], s[0:1], exec
	s_cselect_b32 s25, s39, s45
	s_cselect_b32 s61, s38, s44
	s_ashr_i32 s37, s36, 31
	s_lshl_b64 s[40:41], s[36:37], 19
	v_readlane_b32 s48, v254, 0
	v_readlane_b32 s49, v254, 1
	s_add_u32 s40, s48, s40
	s_addc_u32 s41, s49, s41
	s_and_b64 s[48:49], s[0:1], exec
	s_cselect_b32 s37, s41, s47
	s_cselect_b32 s62, s40, s46
	s_add_u32 s44, s44, 0x40080
	s_addc_u32 s45, s45, 0
	s_add_u32 s63, s46, 0x100
	v_mov_b32_e32 v0, 0
	s_addc_u32 s64, s47, 0
	s_mov_b32 s65, -2
	v_mov_b32_e32 v1, v0
	v_mov_b32_e32 v2, v0
	v_mov_b32_e32 v3, v0
	v_mov_b32_e32 v4, v0
	v_mov_b32_e32 v5, v0
	v_mov_b32_e32 v6, v0
	v_mov_b32_e32 v7, v0
	v_mov_b32_e32 v12, v0
	v_mov_b32_e32 v13, v0
	v_mov_b32_e32 v14, v0
	v_mov_b32_e32 v15, v0
	v_mov_b32_e32 v20, v0
	v_mov_b32_e32 v21, v0
	v_mov_b32_e32 v22, v0
	v_mov_b32_e32 v23, v0
	v_mov_b32_e32 v28, v0
	v_mov_b32_e32 v29, v0
	v_mov_b32_e32 v30, v0
	v_mov_b32_e32 v31, v0
	v_mov_b32_e32 v36, v0
	v_mov_b32_e32 v37, v0
	v_mov_b32_e32 v38, v0
	v_mov_b32_e32 v39, v0
	v_mov_b32_e32 v44, v0
	v_mov_b32_e32 v45, v0
	v_mov_b32_e32 v46, v0
	v_mov_b32_e32 v47, v0
	v_mov_b32_e32 v52, v0
	v_mov_b32_e32 v53, v0
	v_mov_b32_e32 v54, v0
	v_mov_b32_e32 v55, v0
	v_mov_b32_e32 v8, v0
	v_mov_b32_e32 v9, v0
	v_mov_b32_e32 v10, v0
	v_mov_b32_e32 v11, v0
	v_mov_b32_e32 v16, v0
	v_mov_b32_e32 v17, v0
	v_mov_b32_e32 v18, v0
	v_mov_b32_e32 v19, v0
	v_mov_b32_e32 v24, v0
	v_mov_b32_e32 v25, v0
	v_mov_b32_e32 v26, v0
	v_mov_b32_e32 v27, v0
	v_mov_b32_e32 v32, v0
	v_mov_b32_e32 v33, v0
	v_mov_b32_e32 v34, v0
	v_mov_b32_e32 v35, v0
	v_mov_b32_e32 v40, v0
	v_mov_b32_e32 v41, v0
	v_mov_b32_e32 v42, v0
	v_mov_b32_e32 v43, v0
	v_mov_b32_e32 v48, v0
	v_mov_b32_e32 v49, v0
	v_mov_b32_e32 v50, v0
	v_mov_b32_e32 v51, v0
	v_mov_b32_e32 v56, v0
	v_mov_b32_e32 v57, v0
	v_mov_b32_e32 v58, v0
	v_mov_b32_e32 v59, v0
	v_mov_b32_e32 v60, v0
	v_mov_b32_e32 v61, v0
	v_mov_b32_e32 v62, v0
	v_mov_b32_e32 v63, v0
	v_mov_b32_e32 v64, v0
	v_mov_b32_e32 v65, v0
	v_mov_b32_e32 v66, v0
	v_mov_b32_e32 v67, v0
	v_mov_b32_e32 v68, v0
	v_mov_b32_e32 v69, v0
	v_mov_b32_e32 v70, v0
	v_mov_b32_e32 v71, v0
	v_mov_b32_e32 v76, v0
	v_mov_b32_e32 v77, v0
	v_mov_b32_e32 v78, v0
	v_mov_b32_e32 v79, v0
	v_mov_b32_e32 v84, v0
	v_mov_b32_e32 v85, v0
	v_mov_b32_e32 v86, v0
	v_mov_b32_e32 v87, v0
	v_mov_b32_e32 v92, v0
	v_mov_b32_e32 v93, v0
	v_mov_b32_e32 v94, v0
	v_mov_b32_e32 v95, v0
	v_mov_b32_e32 v100, v0
	v_mov_b32_e32 v101, v0
	v_mov_b32_e32 v102, v0
	v_mov_b32_e32 v103, v0
	v_mov_b32_e32 v104, v0
	v_mov_b32_e32 v105, v0
	v_mov_b32_e32 v106, v0
	v_mov_b32_e32 v107, v0
	v_mov_b32_e32 v108, v0
	v_mov_b32_e32 v109, v0
	v_mov_b32_e32 v110, v0
	v_mov_b32_e32 v111, v0
	v_mov_b32_e32 v72, v0
	v_mov_b32_e32 v73, v0
	v_mov_b32_e32 v74, v0
	v_mov_b32_e32 v75, v0
	v_mov_b32_e32 v80, v0
	v_mov_b32_e32 v81, v0
	v_mov_b32_e32 v82, v0
	v_mov_b32_e32 v83, v0
	v_mov_b32_e32 v88, v0
	v_mov_b32_e32 v89, v0
	v_mov_b32_e32 v90, v0
	v_mov_b32_e32 v91, v0
	v_mov_b32_e32 v96, v0
	v_mov_b32_e32 v97, v0
	v_mov_b32_e32 v98, v0
	v_mov_b32_e32 v99, v0
	v_mov_b32_e32 v112, v0
	v_mov_b32_e32 v113, v0
	v_mov_b32_e32 v114, v0
	v_mov_b32_e32 v115, v0
	v_mov_b32_e32 v116, v0
	v_mov_b32_e32 v117, v0
	v_mov_b32_e32 v118, v0
	v_mov_b32_e32 v119, v0
	v_mov_b32_e32 v120, v0
	v_mov_b32_e32 v121, v0
	v_mov_b32_e32 v122, v0
	v_mov_b32_e32 v123, v0
	v_mov_b32_e32 v124, v0
	v_mov_b32_e32 v125, v0
	v_mov_b32_e32 v126, v0
	v_mov_b32_e32 v127, v0
	.p2align 6

;     ...
;         const bool has_next = S.next(ui + 1, nxt);
;         const bool nrev = ZIGZAG && (((ui + 1) & 1) != 0);
;         const ptrdiff_t nk = has_next ? (nrev ? -kfwd : kfwd) : ck, noff = (has_next && nrev) ? kspan : 0;
;         const char* nA = has_next ? (const char*)g.A + (size_t)nxt.pm * tstep + noff : cA; const char* nB = has_next ? (const char*)g.Bt + (size_t)nxt.pn * tstep + noff : cB;
;         for (int t = 0; t < nt; t += 2) {
;             const bool last = (t == nt - 2);
;             const char* a1 = cA + (ptrdiff_t)(t + 1) * ck;
;             const char* a2 = last ? nA : cA + (ptrdiff_t)(t + 2) * ck; const char* b2 = last ? nB : cB + (ptrdiff_t)(t + 2) * ck;
;             const ptrdiff_t k3 = last ? nk : ck;
;             const char* a3 = a2 + k3; const char* b3 = b2 + k3;
;     ...
;         for (int a = 0; a < 2; ++a)
; #pragma unroll
;             for (int b = 0; b < 2; ++b)
; #pragma unroll
;                 for (int m = 0; m < 4; ++m)
; #pragma unroll
;                     for (int n = 0; n < 2; ++n) acc[a][b][m][n] = (f32x4){0.f, 0.f, 0.f, 0.f};
;         cur = nxt; cA = nA; cB = nB; ck = nk; ++ui;
.LBB0_810:
	s_ashr_i32 s37, s36, 31
	s_lshl_b64 s[40:41], s[36:37], 19
	s_add_u32 s40, s74, s40
	s_addc_u32 s41, s75, s41
	s_and_b64 s[42:43], s[0:1], exec
	s_cselect_b32 s37, s41, s47
	s_cselect_b32 s63, s40, s46
	s_ashr_i32 s39, s38, 31
	s_lshl_b64 s[42:43], s[38:39], 19
	v_readlane_b32 s50, v254, 2
	v_readlane_b32 s51, v254, 3
	s_add_u32 s42, s50, s42
	s_addc_u32 s43, s51, s43
	s_and_b64 s[50:51], s[0:1], exec
	s_cselect_b32 s39, s43, s49
	s_cselect_b32 s64, s42, s48
	s_add_u32 s46, s46, 0x40080
	s_addc_u32 s47, s47, 0
	s_add_u32 s65, s48, 0x100
	v_mov_b32_e32 v0, 0
	s_addc_u32 s66, s49, 0
	s_mov_b32 s67, -2
	v_mov_b32_e32 v1, v0
	v_mov_b32_e32 v2, v0
	v_mov_b32_e32 v3, v0
	v_mov_b32_e32 v4, v0
	v_mov_b32_e32 v5, v0
	v_mov_b32_e32 v6, v0
	v_mov_b32_e32 v7, v0
	v_mov_b32_e32 v16, v0
	v_mov_b32_e32 v17, v0
	v_mov_b32_e32 v18, v0
	v_mov_b32_e32 v19, v0
	v_mov_b32_e32 v20, v0
	v_mov_b32_e32 v21, v0
	v_mov_b32_e32 v22, v0
	v_mov_b32_e32 v23, v0
	v_mov_b32_e32 v32, v0
	v_mov_b32_e32 v33, v0
	v_mov_b32_e32 v34, v0
	v_mov_b32_e32 v35, v0
	v_mov_b32_e32 v36, v0
	v_mov_b32_e32 v37, v0
	v_mov_b32_e32 v38, v0
	v_mov_b32_e32 v39, v0
	v_mov_b32_e32 v48, v0
	v_mov_b32_e32 v49, v0
	v_mov_b32_e32 v50, v0
	v_mov_b32_e32 v51, v0
	v_mov_b32_e32 v52, v0
	v_mov_b32_e32 v53, v0
	v_mov_b32_e32 v54, v0
	v_mov_b32_e32 v55, v0
	v_mov_b32_e32 v8, v0
	v_mov_b32_e32 v9, v0
	v_mov_b32_e32 v10, v0
	v_mov_b32_e32 v11, v0
	v_mov_b32_e32 v12, v0
	v_mov_b32_e32 v13, v0
	v_mov_b32_e32 v14, v0
	v_mov_b32_e32 v15, v0
	v_mov_b32_e32 v24, v0
	v_mov_b32_e32 v25, v0
	v_mov_b32_e32 v26, v0
	v_mov_b32_e32 v27, v0
	v_mov_b32_e32 v28, v0
	v_mov_b32_e32 v29, v0
	v_mov_b32_e32 v30, v0
	v_mov_b32_e32 v31, v0
	v_mov_b32_e32 v40, v0
	v_mov_b32_e32 v41, v0
	v_mov_b32_e32 v42, v0
	v_mov_b32_e32 v43, v0
	v_mov_b32_e32 v44, v0
	v_mov_b32_e32 v45, v0
	v_mov_b32_e32 v46, v0
	v_mov_b32_e32 v47, v0
	v_mov_b32_e32 v56, v0
	v_mov_b32_e32 v57, v0
	v_mov_b32_e32 v58, v0
	v_mov_b32_e32 v59, v0
	v_mov_b32_e32 v60, v0
	v_mov_b32_e32 v61, v0
	v_mov_b32_e32 v62, v0
	v_mov_b32_e32 v63, v0
	v_mov_b32_e32 v64, v0
	v_mov_b32_e32 v65, v0
	v_mov_b32_e32 v66, v0
	v_mov_b32_e32 v67, v0
	v_mov_b32_e32 v68, v0
	v_mov_b32_e32 v69, v0
	v_mov_b32_e32 v70, v0
	v_mov_b32_e32 v71, v0
	v_mov_b32_e32 v80, v0
	v_mov_b32_e32 v81, v0
	v_mov_b32_e32 v82, v0
	v_mov_b32_e32 v83, v0
	v_mov_b32_e32 v84, v0
	v_mov_b32_e32 v85, v0
	v_mov_b32_e32 v86, v0
	v_mov_b32_e32 v87, v0
	v_mov_b32_e32 v96, v0
	v_mov_b32_e32 v97, v0
	v_mov_b32_e32 v98, v0
	v_mov_b32_e32 v99, v0
	v_mov_b32_e32 v100, v0
	v_mov_b32_e32 v101, v0
	v_mov_b32_e32 v102, v0
	v_mov_b32_e32 v103, v0
	v_mov_b32_e32 v112, v0
	v_mov_b32_e32 v113, v0
	v_mov_b32_e32 v114, v0
	v_mov_b32_e32 v115, v0
	v_mov_b32_e32 v116, v0
	v_mov_b32_e32 v117, v0
	v_mov_b32_e32 v118, v0
	v_mov_b32_e32 v119, v0
	v_mov_b32_e32 v72, v0
	v_mov_b32_e32 v73, v0
	v_mov_b32_e32 v74, v0
	v_mov_b32_e32 v75, v0
	v_mov_b32_e32 v76, v0
	v_mov_b32_e32 v77, v0
	v_mov_b32_e32 v78, v0
	v_mov_b32_e32 v79, v0
	v_mov_b32_e32 v88, v0
	v_mov_b32_e32 v89, v0
	v_mov_b32_e32 v90, v0
	v_mov_b32_e32 v91, v0
	v_mov_b32_e32 v92, v0
	v_mov_b32_e32 v93, v0
	v_mov_b32_e32 v94, v0
	v_mov_b32_e32 v95, v0
	v_mov_b32_e32 v104, v0
	v_mov_b32_e32 v105, v0
	v_mov_b32_e32 v106, v0
	v_mov_b32_e32 v107, v0
	v_mov_b32_e32 v108, v0
	v_mov_b32_e32 v109, v0
	v_mov_b32_e32 v110, v0
	v_mov_b32_e32 v111, v0
	v_mov_b32_e32 v120, v0
	v_mov_b32_e32 v121, v0
	v_mov_b32_e32 v122, v0
	v_mov_b32_e32 v123, v0
	v_mov_b32_e32 v124, v0
	v_mov_b32_e32 v125, v0
	v_mov_b32_e32 v126, v0
	v_mov_b32_e32 v127, v0
	.p2align 6

;     ...
;         const bool has_next = S.next(ui + 1, nxt);
;         const bool nrev = ZIGZAG && (((ui + 1) & 1) != 0);
;         const ptrdiff_t nk = has_next ? (nrev ? -kfwd : kfwd) : ck, noff = (has_next && nrev) ? kspan : 0;
;         const char* nA = has_next ? (const char*)g.A + (size_t)nxt.pm * tstep + noff : cA; const char* nB = has_next ? (const char*)g.Bt + (size_t)nxt.pn * tstep + noff : cB;
;         for (int t = 0; t < nt; t += 2) {
;             const bool last = (t == nt - 2);
;             const char* a1 = cA + (ptrdiff_t)(t + 1) * ck;
;             const char* a2 = last ? nA : cA + (ptrdiff_t)(t + 2) * ck; const char* b2 = last ? nB : cB + (ptrdiff_t)(t + 2) * ck;
;             const ptrdiff_t k3 = last ? nk : ck;
;             const char* a3 = a2 + k3; const char* b3 = b2 + k3;
;     ...
;         for (int a = 0; a < 2; ++a)
; #pragma unroll
;             for (int b = 0; b < 2; ++b)
; #pragma unroll
;                 for (int m = 0; m < 4; ++m)
; #pragma unroll
;                     for (int n = 0; n < 2; ++n) acc[a][b][m][n] = (f32x4){0.f, 0.f, 0.f, 0.f};
;         cur = nxt; cA = nA; cB = nB; ck = nk; ++ui;
.LBB0_885:
	s_ashr_i32 s15, s14, 31
	s_lshl_b64 s[36:37], s[14:15], 19
	s_add_u32 s36, s26, s36
	s_addc_u32 s37, s27, s37
	s_and_b64 s[38:39], s[0:1], exec
	s_cselect_b32 s15, s37, s43
	s_cselect_b32 s59, s36, s42
	s_ashr_i32 s25, s24, 31
	s_lshl_b64 s[38:39], s[24:25], 19
	s_add_u32 s38, s76, s38
	s_addc_u32 s39, s77, s39
	s_and_b64 s[46:47], s[0:1], exec
	s_cselect_b32 s25, s39, s45
	s_cselect_b32 s60, s38, s44
	s_add_u32 s42, s42, 0x40080
	s_addc_u32 s43, s43, 0
	s_add_u32 s61, s44, 0x100
	v_mov_b32_e32 v0, 0
	s_addc_u32 s62, s45, 0
	s_mov_b32 s63, -2
	v_mov_b32_e32 v1, v0
	v_mov_b32_e32 v2, v0
	v_mov_b32_e32 v3, v0
	v_mov_b32_e32 v4, v0
	v_mov_b32_e32 v5, v0
	v_mov_b32_e32 v6, v0
	v_mov_b32_e32 v7, v0
	v_mov_b32_e32 v16, v0
	v_mov_b32_e32 v17, v0
	v_mov_b32_e32 v18, v0
	v_mov_b32_e32 v19, v0
	v_mov_b32_e32 v20, v0
	v_mov_b32_e32 v21, v0
	v_mov_b32_e32 v22, v0
	v_mov_b32_e32 v23, v0
	v_mov_b32_e32 v32, v0
	v_mov_b32_e32 v33, v0
	v_mov_b32_e32 v34, v0
	v_mov_b32_e32 v35, v0
	v_mov_b32_e32 v36, v0
	v_mov_b32_e32 v37, v0
	v_mov_b32_e32 v38, v0
	v_mov_b32_e32 v39, v0
	v_mov_b32_e32 v48, v0
	v_mov_b32_e32 v49, v0
	v_mov_b32_e32 v50, v0
	v_mov_b32_e32 v51, v0
	v_mov_b32_e32 v52, v0
	v_mov_b32_e32 v53, v0
	v_mov_b32_e32 v54, v0
	v_mov_b32_e32 v55, v0
	v_mov_b32_e32 v8, v0
	v_mov_b32_e32 v9, v0
	v_mov_b32_e32 v10, v0
	v_mov_b32_e32 v11, v0
	v_mov_b32_e32 v12, v0
	v_mov_b32_e32 v13, v0
	v_mov_b32_e32 v14, v0
	v_mov_b32_e32 v15, v0
	v_mov_b32_e32 v24, v0
	v_mov_b32_e32 v25, v0
	v_mov_b32_e32 v26, v0
	v_mov_b32_e32 v27, v0
	v_mov_b32_e32 v28, v0
	v_mov_b32_e32 v29, v0
	v_mov_b32_e32 v30, v0
	v_mov_b32_e32 v31, v0
	v_mov_b32_e32 v40, v0
	v_mov_b32_e32 v41, v0
	v_mov_b32_e32 v42, v0
	v_mov_b32_e32 v43, v0
	v_mov_b32_e32 v44, v0
	v_mov_b32_e32 v45, v0
	v_mov_b32_e32 v46, v0
	v_mov_b32_e32 v47, v0
	v_mov_b32_e32 v56, v0
	v_mov_b32_e32 v57, v0
	v_mov_b32_e32 v58, v0
	v_mov_b32_e32 v59, v0
	v_mov_b32_e32 v60, v0
	v_mov_b32_e32 v61, v0
	v_mov_b32_e32 v62, v0
	v_mov_b32_e32 v63, v0
	v_mov_b32_e32 v64, v0
	v_mov_b32_e32 v65, v0
	v_mov_b32_e32 v66, v0
	v_mov_b32_e32 v67, v0
	v_mov_b32_e32 v68, v0
	v_mov_b32_e32 v69, v0
	v_mov_b32_e32 v70, v0
	v_mov_b32_e32 v71, v0
	v_mov_b32_e32 v80, v0
	v_mov_b32_e32 v81, v0
	v_mov_b32_e32 v82, v0
	v_mov_b32_e32 v83, v0
	v_mov_b32_e32 v84, v0
	v_mov_b32_e32 v85, v0
	v_mov_b32_e32 v86, v0
	v_mov_b32_e32 v87, v0
	v_mov_b32_e32 v96, v0
	v_mov_b32_e32 v97, v0
	v_mov_b32_e32 v98, v0
	v_mov_b32_e32 v99, v0
	v_mov_b32_e32 v100, v0
	v_mov_b32_e32 v101, v0
	v_mov_b32_e32 v102, v0
	v_mov_b32_e32 v103, v0
	v_mov_b32_e32 v112, v0
	v_mov_b32_e32 v113, v0
	v_mov_b32_e32 v114, v0
	v_mov_b32_e32 v115, v0
	v_mov_b32_e32 v116, v0
	v_mov_b32_e32 v117, v0
	v_mov_b32_e32 v118, v0
	v_mov_b32_e32 v119, v0
	v_mov_b32_e32 v72, v0
	v_mov_b32_e32 v73, v0
	v_mov_b32_e32 v74, v0
	v_mov_b32_e32 v75, v0
	v_mov_b32_e32 v76, v0
	v_mov_b32_e32 v77, v0
	v_mov_b32_e32 v78, v0
	v_mov_b32_e32 v79, v0
	v_mov_b32_e32 v88, v0
	v_mov_b32_e32 v89, v0
	v_mov_b32_e32 v90, v0
	v_mov_b32_e32 v91, v0
	v_mov_b32_e32 v92, v0
	v_mov_b32_e32 v93, v0
	v_mov_b32_e32 v94, v0
	v_mov_b32_e32 v95, v0
	v_mov_b32_e32 v104, v0
	v_mov_b32_e32 v105, v0
	v_mov_b32_e32 v106, v0
	v_mov_b32_e32 v107, v0
	v_mov_b32_e32 v108, v0
	v_mov_b32_e32 v109, v0
	v_mov_b32_e32 v110, v0
	v_mov_b32_e32 v111, v0
	v_mov_b32_e32 v120, v0
	v_mov_b32_e32 v121, v0
	v_mov_b32_e32 v122, v0
	v_mov_b32_e32 v123, v0
	v_mov_b32_e32 v124, v0
	v_mov_b32_e32 v125, v0
	v_mov_b32_e32 v126, v0
	v_mov_b32_e32 v127, v0
	.p2align 6

;     ...
;         const bool has_next = S.next(ui + 1, nxt);
;         const bool nrev = ZIGZAG && (((ui + 1) & 1) != 0);
;         const ptrdiff_t nk = has_next ? (nrev ? -kfwd : kfwd) : ck, noff = (has_next && nrev) ? kspan : 0;
;         const char* nA = has_next ? (const char*)g.A + (size_t)nxt.pm * tstep + noff : cA; const char* nB = has_next ? (const char*)g.Bt + (size_t)nxt.pn * tstep + noff : cB;
;         for (int t = 0; t < nt; t += 2) {
;             const bool last = (t == nt - 2);
;             const char* a1 = cA + (ptrdiff_t)(t + 1) * ck;
;             const char* a2 = last ? nA : cA + (ptrdiff_t)(t + 2) * ck; const char* b2 = last ? nB : cB + (ptrdiff_t)(t + 2) * ck;
;             const ptrdiff_t k3 = last ? nk : ck;
;             const char* a3 = a2 + k3; const char* b3 = b2 + k3;
;     ...
;         for (int a = 0; a < 2; ++a)
; #pragma unroll
;             for (int b = 0; b < 2; ++b)
; #pragma unroll
;                 for (int m = 0; m < 4; ++m)
; #pragma unroll
;                     for (int n = 0; n < 2; ++n) acc[a][b][m][n] = (f32x4){0.f, 0.f, 0.f, 0.f};
;         cur = nxt; cA = nA; cB = nB; ck = nk; ++ui;
.LBB0_1070:
	s_ashr_i32 s13, s12, 31
	s_lshl_b64 s[22:23], s[12:13], 19
	s_add_u32 s22, s34, s22
	s_addc_u32 s23, s35, s23
	s_and_b64 s[24:25], s[0:1], exec
	s_cselect_b32 s13, s23, s37
	s_cselect_b32 s27, s22, s36
	s_ashr_i32 s15, s14, 31
	s_lshl_b64 s[24:25], s[14:15], 19
	s_add_u32 s24, s70, s24
	s_addc_u32 s25, s71, s25
	s_and_b64 s[40:41], s[0:1], exec
	s_cselect_b32 s15, s25, s39
	s_cselect_b32 s59, s24, s38
	s_add_u32 s36, s36, 0x40080
	s_addc_u32 s37, s37, 0
	s_add_u32 s60, s38, 0x100
	v_mov_b32_e32 v0, 0
	s_addc_u32 s61, s39, 0
	s_mov_b32 s62, -2
	v_mov_b32_e32 v1, v0
	v_mov_b32_e32 v2, v0
	v_mov_b32_e32 v3, v0
	v_mov_b32_e32 v4, v0
	v_mov_b32_e32 v5, v0
	v_mov_b32_e32 v6, v0
	v_mov_b32_e32 v7, v0
	v_mov_b32_e32 v16, v0
	v_mov_b32_e32 v17, v0
	v_mov_b32_e32 v18, v0
	v_mov_b32_e32 v19, v0
	v_mov_b32_e32 v20, v0
	v_mov_b32_e32 v21, v0
	v_mov_b32_e32 v22, v0
	v_mov_b32_e32 v23, v0
	v_mov_b32_e32 v32, v0
	v_mov_b32_e32 v33, v0
	v_mov_b32_e32 v34, v0
	v_mov_b32_e32 v35, v0
	v_mov_b32_e32 v36, v0
	v_mov_b32_e32 v37, v0
	v_mov_b32_e32 v38, v0
	v_mov_b32_e32 v39, v0
	v_mov_b32_e32 v48, v0
	v_mov_b32_e32 v49, v0
	v_mov_b32_e32 v50, v0
	v_mov_b32_e32 v51, v0
	v_mov_b32_e32 v52, v0
	v_mov_b32_e32 v53, v0
	v_mov_b32_e32 v54, v0
	v_mov_b32_e32 v55, v0
	v_mov_b32_e32 v8, v0
	v_mov_b32_e32 v9, v0
	v_mov_b32_e32 v10, v0
	v_mov_b32_e32 v11, v0
	v_mov_b32_e32 v12, v0
	v_mov_b32_e32 v13, v0
	v_mov_b32_e32 v14, v0
	v_mov_b32_e32 v15, v0
	v_mov_b32_e32 v24, v0
	v_mov_b32_e32 v25, v0
	v_mov_b32_e32 v26, v0
	v_mov_b32_e32 v27, v0
	v_mov_b32_e32 v28, v0
	v_mov_b32_e32 v29, v0
	v_mov_b32_e32 v30, v0
	v_mov_b32_e32 v31, v0
	v_mov_b32_e32 v40, v0
	v_mov_b32_e32 v41, v0
	v_mov_b32_e32 v42, v0
	v_mov_b32_e32 v43, v0
	v_mov_b32_e32 v44, v0
	v_mov_b32_e32 v45, v0
	v_mov_b32_e32 v46, v0
	v_mov_b32_e32 v47, v0
	v_mov_b32_e32 v56, v0
	v_mov_b32_e32 v57, v0
	v_mov_b32_e32 v58, v0
	v_mov_b32_e32 v59, v0
	v_mov_b32_e32 v60, v0
	v_mov_b32_e32 v61, v0
	v_mov_b32_e32 v62, v0
	v_mov_b32_e32 v63, v0
	v_mov_b32_e32 v64, v0
	v_mov_b32_e32 v65, v0
	v_mov_b32_e32 v66, v0
	v_mov_b32_e32 v67, v0
	v_mov_b32_e32 v68, v0
	v_mov_b32_e32 v69, v0
	v_mov_b32_e32 v70, v0
	v_mov_b32_e32 v71, v0
	v_mov_b32_e32 v80, v0
	v_mov_b32_e32 v81, v0
	v_mov_b32_e32 v82, v0
	v_mov_b32_e32 v83, v0
	v_mov_b32_e32 v84, v0
	v_mov_b32_e32 v85, v0
	v_mov_b32_e32 v86, v0
	v_mov_b32_e32 v87, v0
	v_mov_b32_e32 v96, v0
	v_mov_b32_e32 v97, v0
	v_mov_b32_e32 v98, v0
	v_mov_b32_e32 v99, v0
	v_mov_b32_e32 v100, v0
	v_mov_b32_e32 v101, v0
	v_mov_b32_e32 v102, v0
	v_mov_b32_e32 v103, v0
	v_mov_b32_e32 v112, v0
	v_mov_b32_e32 v113, v0
	v_mov_b32_e32 v114, v0
	v_mov_b32_e32 v115, v0
	v_mov_b32_e32 v116, v0
	v_mov_b32_e32 v117, v0
	v_mov_b32_e32 v118, v0
	v_mov_b32_e32 v119, v0
	v_mov_b32_e32 v72, v0
	v_mov_b32_e32 v73, v0
	v_mov_b32_e32 v74, v0
	v_mov_b32_e32 v75, v0
	v_mov_b32_e32 v76, v0
	v_mov_b32_e32 v77, v0
	v_mov_b32_e32 v78, v0
	v_mov_b32_e32 v79, v0
	v_mov_b32_e32 v88, v0
	v_mov_b32_e32 v89, v0
	v_mov_b32_e32 v90, v0
	v_mov_b32_e32 v91, v0
	v_mov_b32_e32 v92, v0
	v_mov_b32_e32 v93, v0
	v_mov_b32_e32 v94, v0
	v_mov_b32_e32 v95, v0
	v_mov_b32_e32 v104, v0
	v_mov_b32_e32 v105, v0
	v_mov_b32_e32 v106, v0
	v_mov_b32_e32 v107, v0
	v_mov_b32_e32 v108, v0
	v_mov_b32_e32 v109, v0
	v_mov_b32_e32 v110, v0
	v_mov_b32_e32 v111, v0
	v_mov_b32_e32 v120, v0
	v_mov_b32_e32 v121, v0
	v_mov_b32_e32 v122, v0
	v_mov_b32_e32 v123, v0
	v_mov_b32_e32 v124, v0
	v_mov_b32_e32 v125, v0
	v_mov_b32_e32 v126, v0
	v_mov_b32_e32 v127, v0
	.p2align 6

;     ...
;             const char* a1 = cA + (ptrdiff_t)(t + 1) * ck;
;             const char* a2 = last ? nA : cA + (ptrdiff_t)(t + 2) * ck; const char* b2 = last ? nB : cB + (ptrdiff_t)(t + 2) * ck;
;             const ptrdiff_t k3 = last ? nk : ck;
;             const char* a3 = a2 + k3; const char* b3 = b2 + k3;
;     ...
;         for (int a = 0; a < 2; ++a)
; #pragma unroll
;             for (int b = 0; b < 2; ++b)
; #pragma unroll
;                 for (int m = 0; m < 4; ++m)
; #pragma unroll
;                     for (int n = 0; n < 2; ++n) acc[a][b][m][n] = (f32x4){0.f, 0.f, 0.f, 0.f};
;         cur = nxt; cA = nA; cB = nB; ck = nk; ++ui;
.LBB0_1155:
	s_add_u32 s24, s24, 0xb0080
	s_addc_u32 s25, s25, 0
	s_add_u32 s53, s26, 0x100
	v_mov_b32_e32 v0, 0
	s_addc_u32 s54, s27, 0
	s_mov_b32 s55, -2
	v_mov_b32_e32 v1, v0
	v_mov_b32_e32 v2, v0
	v_mov_b32_e32 v3, v0
	v_mov_b32_e32 v4, v0
	v_mov_b32_e32 v5, v0
	v_mov_b32_e32 v6, v0
	v_mov_b32_e32 v7, v0
	v_mov_b32_e32 v16, v0
	v_mov_b32_e32 v17, v0
	v_mov_b32_e32 v18, v0
	v_mov_b32_e32 v19, v0
	v_mov_b32_e32 v20, v0
	v_mov_b32_e32 v21, v0
	v_mov_b32_e32 v22, v0
	v_mov_b32_e32 v23, v0
	v_mov_b32_e32 v32, v0
	v_mov_b32_e32 v33, v0
	v_mov_b32_e32 v34, v0
	v_mov_b32_e32 v35, v0
	v_mov_b32_e32 v36, v0
	v_mov_b32_e32 v37, v0
	v_mov_b32_e32 v38, v0
	v_mov_b32_e32 v39, v0
	v_mov_b32_e32 v48, v0
	v_mov_b32_e32 v49, v0
	v_mov_b32_e32 v50, v0
	v_mov_b32_e32 v51, v0
	v_mov_b32_e32 v52, v0
	v_mov_b32_e32 v53, v0
	v_mov_b32_e32 v54, v0
	v_mov_b32_e32 v55, v0
	v_mov_b32_e32 v8, v0
	v_mov_b32_e32 v9, v0
	v_mov_b32_e32 v10, v0
	v_mov_b32_e32 v11, v0
	v_mov_b32_e32 v12, v0
	v_mov_b32_e32 v13, v0
	v_mov_b32_e32 v14, v0
	v_mov_b32_e32 v15, v0
	v_mov_b32_e32 v24, v0
	v_mov_b32_e32 v25, v0
	v_mov_b32_e32 v26, v0
	v_mov_b32_e32 v27, v0
	v_mov_b32_e32 v28, v0
	v_mov_b32_e32 v29, v0
	v_mov_b32_e32 v30, v0
	v_mov_b32_e32 v31, v0
	v_mov_b32_e32 v40, v0
	v_mov_b32_e32 v41, v0
	v_mov_b32_e32 v42, v0
	v_mov_b32_e32 v43, v0
	v_mov_b32_e32 v44, v0
	v_mov_b32_e32 v45, v0
	v_mov_b32_e32 v46, v0
	v_mov_b32_e32 v47, v0
	v_mov_b32_e32 v56, v0
	v_mov_b32_e32 v57, v0
	v_mov_b32_e32 v58, v0
	v_mov_b32_e32 v59, v0
	v_mov_b32_e32 v60, v0
	v_mov_b32_e32 v61, v0
	v_mov_b32_e32 v62, v0
	v_mov_b32_e32 v63, v0
	v_mov_b32_e32 v64, v0
	v_mov_b32_e32 v65, v0
	v_mov_b32_e32 v66, v0
	v_mov_b32_e32 v67, v0
	v_mov_b32_e32 v68, v0
	v_mov_b32_e32 v69, v0
	v_mov_b32_e32 v70, v0
	v_mov_b32_e32 v71, v0
	v_mov_b32_e32 v80, v0
	v_mov_b32_e32 v81, v0
	v_mov_b32_e32 v82, v0
	v_mov_b32_e32 v83, v0
	v_mov_b32_e32 v84, v0
	v_mov_b32_e32 v85, v0
	v_mov_b32_e32 v86, v0
	v_mov_b32_e32 v87, v0
	v_mov_b32_e32 v96, v0
	v_mov_b32_e32 v97, v0
	v_mov_b32_e32 v98, v0
	v_mov_b32_e32 v99, v0
	v_mov_b32_e32 v100, v0
	v_mov_b32_e32 v101, v0
	v_mov_b32_e32 v102, v0
	v_mov_b32_e32 v103, v0
	v_mov_b32_e32 v112, v0
	v_mov_b32_e32 v113, v0
	v_mov_b32_e32 v114, v0
	v_mov_b32_e32 v115, v0
	v_mov_b32_e32 v116, v0
	v_mov_b32_e32 v117, v0
	v_mov_b32_e32 v118, v0
	v_mov_b32_e32 v119, v0
	v_mov_b32_e32 v72, v0
	v_mov_b32_e32 v73, v0
	v_mov_b32_e32 v74, v0
	v_mov_b32_e32 v75, v0
	v_mov_b32_e32 v76, v0
	v_mov_b32_e32 v77, v0
	v_mov_b32_e32 v78, v0
	v_mov_b32_e32 v79, v0
	v_mov_b32_e32 v88, v0
	v_mov_b32_e32 v89, v0
	v_mov_b32_e32 v90, v0
	v_mov_b32_e32 v91, v0
	v_mov_b32_e32 v92, v0
	v_mov_b32_e32 v93, v0
	v_mov_b32_e32 v94, v0
	v_mov_b32_e32 v95, v0
	v_mov_b32_e32 v104, v0
	v_mov_b32_e32 v105, v0
	v_mov_b32_e32 v106, v0
	v_mov_b32_e32 v107, v0
	v_mov_b32_e32 v108, v0
	v_mov_b32_e32 v109, v0
	v_mov_b32_e32 v110, v0
	v_mov_b32_e32 v111, v0
	v_mov_b32_e32 v120, v0
	v_mov_b32_e32 v121, v0
	v_mov_b32_e32 v122, v0
	v_mov_b32_e32 v123, v0
	v_mov_b32_e32 v124, v0
	v_mov_b32_e32 v125, v0
	v_mov_b32_e32 v126, v0
	v_mov_b32_e32 v127, v0
	.p2align 6

;     ...
;         const bool has_next = S.next(ui + 1, nxt);
;         const bool nrev = ZIGZAG && (((ui + 1) & 1) != 0);
;         const ptrdiff_t nk = has_next ? (nrev ? -kfwd : kfwd) : ck, noff = (has_next && nrev) ? kspan : 0;
;         const char* nA = has_next ? (const char*)g.A + (size_t)nxt.pm * tstep + noff : cA; const char* nB = has_next ? (const char*)g.Bt + (size_t)nxt.pn * tstep + noff : cB;
;         for (int t = 0; t < nt; t += 2) {
;             const bool last = (t == nt - 2);
;             const char* a1 = cA + (ptrdiff_t)(t + 1) * ck;
;             const char* a2 = last ? nA : cA + (ptrdiff_t)(t + 2) * ck; const char* b2 = last ? nB : cB + (ptrdiff_t)(t + 2) * ck;
;             const ptrdiff_t k3 = last ? nk : ck;
;             const char* a3 = a2 + k3; const char* b3 = b2 + k3;
;     ...
;         for (int a = 0; a < 2; ++a)
; #pragma unroll
;             for (int b = 0; b < 2; ++b)
; #pragma unroll
;                 for (int m = 0; m < 4; ++m)
; #pragma unroll
;                     for (int n = 0; n < 2; ++n) acc[a][b][m][n] = (f32x4){0.f, 0.f, 0.f, 0.f};
;         cur = nxt; cA = nA; cB = nB; ck = nk; ++ui;
.LBB0_1352:
	s_ashr_i32 s25, s24, 31
	s_lshl_b64 s[36:37], s[24:25], 19
	s_add_u32 s36, s34, s36
	s_addc_u32 s37, s35, s37
	s_and_b64 s[38:39], s[0:1], exec
	s_cselect_b32 s25, s37, s43
	s_cselect_b32 s41, s36, s42
	s_ashr_i32 s27, s26, 31
	s_lshl_b64 s[38:39], s[26:27], 19
	s_add_u32 s38, s86, s38
	s_addc_u32 s39, s87, s39
	s_and_b64 s[46:47], s[0:1], exec
	s_cselect_b32 s27, s39, s45
	s_cselect_b32 s67, s38, s44
	s_add_u32 s42, s42, 0x40080
	s_addc_u32 s43, s43, 0
	s_add_u32 s68, s44, 0x100
	v_mov_b32_e32 v0, 0
	s_addc_u32 s69, s45, 0
	s_mov_b32 s70, -2
	v_mov_b32_e32 v1, v0
	v_mov_b32_e32 v2, v0
	v_mov_b32_e32 v3, v0
	v_mov_b32_e32 v4, v0
	v_mov_b32_e32 v5, v0
	v_mov_b32_e32 v6, v0
	v_mov_b32_e32 v7, v0
	v_mov_b32_e32 v16, v0
	v_mov_b32_e32 v17, v0
	v_mov_b32_e32 v18, v0
	v_mov_b32_e32 v19, v0
	v_mov_b32_e32 v20, v0
	v_mov_b32_e32 v21, v0
	v_mov_b32_e32 v22, v0
	v_mov_b32_e32 v23, v0
	v_mov_b32_e32 v32, v0
	v_mov_b32_e32 v33, v0
	v_mov_b32_e32 v34, v0
	v_mov_b32_e32 v35, v0
	v_mov_b32_e32 v36, v0
	v_mov_b32_e32 v37, v0
	v_mov_b32_e32 v38, v0
	v_mov_b32_e32 v39, v0
	v_mov_b32_e32 v48, v0
	v_mov_b32_e32 v49, v0
	v_mov_b32_e32 v50, v0
	v_mov_b32_e32 v51, v0
	v_mov_b32_e32 v52, v0
	v_mov_b32_e32 v53, v0
	v_mov_b32_e32 v54, v0
	v_mov_b32_e32 v55, v0
	v_mov_b32_e32 v8, v0
	v_mov_b32_e32 v9, v0
	v_mov_b32_e32 v10, v0
	v_mov_b32_e32 v11, v0
	v_mov_b32_e32 v12, v0
	v_mov_b32_e32 v13, v0
	v_mov_b32_e32 v14, v0
	v_mov_b32_e32 v15, v0
	v_mov_b32_e32 v24, v0
	v_mov_b32_e32 v25, v0
	v_mov_b32_e32 v26, v0
	v_mov_b32_e32 v27, v0
	v_mov_b32_e32 v28, v0
	v_mov_b32_e32 v29, v0
	v_mov_b32_e32 v30, v0
	v_mov_b32_e32 v31, v0
	v_mov_b32_e32 v40, v0
	v_mov_b32_e32 v41, v0
	v_mov_b32_e32 v42, v0
	v_mov_b32_e32 v43, v0
	v_mov_b32_e32 v44, v0
	v_mov_b32_e32 v45, v0
	v_mov_b32_e32 v46, v0
	v_mov_b32_e32 v47, v0
	v_mov_b32_e32 v56, v0
	v_mov_b32_e32 v57, v0
	v_mov_b32_e32 v58, v0
	v_mov_b32_e32 v59, v0
	v_mov_b32_e32 v60, v0
	v_mov_b32_e32 v61, v0
	v_mov_b32_e32 v62, v0
	v_mov_b32_e32 v63, v0
	v_mov_b32_e32 v64, v0
	v_mov_b32_e32 v65, v0
	v_mov_b32_e32 v66, v0
	v_mov_b32_e32 v67, v0
	v_mov_b32_e32 v68, v0
	v_mov_b32_e32 v69, v0
	v_mov_b32_e32 v70, v0
	v_mov_b32_e32 v71, v0
	v_mov_b32_e32 v80, v0
	v_mov_b32_e32 v81, v0
	v_mov_b32_e32 v82, v0
	v_mov_b32_e32 v83, v0
	v_mov_b32_e32 v84, v0
	v_mov_b32_e32 v85, v0
	v_mov_b32_e32 v86, v0
	v_mov_b32_e32 v87, v0
	v_mov_b32_e32 v96, v0
	v_mov_b32_e32 v97, v0
	v_mov_b32_e32 v98, v0
	v_mov_b32_e32 v99, v0
	v_mov_b32_e32 v100, v0
	v_mov_b32_e32 v101, v0
	v_mov_b32_e32 v102, v0
	v_mov_b32_e32 v103, v0
	v_mov_b32_e32 v112, v0
	v_mov_b32_e32 v113, v0
	v_mov_b32_e32 v114, v0
	v_mov_b32_e32 v115, v0
	v_mov_b32_e32 v116, v0
	v_mov_b32_e32 v117, v0
	v_mov_b32_e32 v118, v0
	v_mov_b32_e32 v119, v0
	v_mov_b32_e32 v72, v0
	v_mov_b32_e32 v73, v0
	v_mov_b32_e32 v74, v0
	v_mov_b32_e32 v75, v0
	v_mov_b32_e32 v76, v0
	v_mov_b32_e32 v77, v0
	v_mov_b32_e32 v78, v0
	v_mov_b32_e32 v79, v0
	v_mov_b32_e32 v88, v0
	v_mov_b32_e32 v89, v0
	v_mov_b32_e32 v90, v0
	v_mov_b32_e32 v91, v0
	v_mov_b32_e32 v92, v0
	v_mov_b32_e32 v93, v0
	v_mov_b32_e32 v94, v0
	v_mov_b32_e32 v95, v0
	v_mov_b32_e32 v104, v0
	v_mov_b32_e32 v105, v0
	v_mov_b32_e32 v106, v0
	v_mov_b32_e32 v107, v0
	v_mov_b32_e32 v108, v0
	v_mov_b32_e32 v109, v0
	v_mov_b32_e32 v110, v0
	v_mov_b32_e32 v111, v0
	v_mov_b32_e32 v120, v0
	v_mov_b32_e32 v121, v0
	v_mov_b32_e32 v122, v0
	v_mov_b32_e32 v123, v0
	v_mov_b32_e32 v124, v0
	v_mov_b32_e32 v125, v0
	v_mov_b32_e32 v126, v0
	v_mov_b32_e32 v127, v0
	.p2align 6

;     ...
;         for (int t = 0; t < nt; t += 2) {
;     ...
;         for (int a = 0; a < 2; ++a)
; #pragma unroll
;             for (int b = 0; b < 2; ++b)
; #pragma unroll
;                 for (int m = 0; m < 4; ++m)
; #pragma unroll
;                     for (int n = 0; n < 2; ++n) acc[a][b][m][n] = (f32x4){0.f, 0.f, 0.f, 0.f};
;         cur = nxt; cA = nA; cB = nB; ck = nk; ++ui;
.LBB0_1387:
	v_mov_b32_e32 v127, 0
	s_and_b64 vcc, exec, s[0:1]
	v_mov_b32_e32 v126, v127
	v_mov_b32_e32 v125, v127
	v_mov_b32_e32 v124, v127
	v_mov_b32_e32 v123, v127
	v_mov_b32_e32 v122, v127
	v_mov_b32_e32 v121, v127
	v_mov_b32_e32 v120, v127
	v_mov_b32_e32 v111, v127
	v_mov_b32_e32 v110, v127
	v_mov_b32_e32 v109, v127
	v_mov_b32_e32 v108, v127
	v_mov_b32_e32 v107, v127
	v_mov_b32_e32 v106, v127
	v_mov_b32_e32 v105, v127
	v_mov_b32_e32 v104, v127
	v_mov_b32_e32 v95, v127
	v_mov_b32_e32 v94, v127
	v_mov_b32_e32 v93, v127
	v_mov_b32_e32 v92, v127
	v_mov_b32_e32 v91, v127
	v_mov_b32_e32 v90, v127
	v_mov_b32_e32 v89, v127
	v_mov_b32_e32 v88, v127
	v_mov_b32_e32 v79, v127
	v_mov_b32_e32 v78, v127
	v_mov_b32_e32 v77, v127
	v_mov_b32_e32 v76, v127
	v_mov_b32_e32 v75, v127
	v_mov_b32_e32 v74, v127
	v_mov_b32_e32 v73, v127
	v_mov_b32_e32 v72, v127
	v_mov_b32_e32 v119, v127
	v_mov_b32_e32 v118, v127
	v_mov_b32_e32 v117, v127
	v_mov_b32_e32 v116, v127
	v_mov_b32_e32 v115, v127
	v_mov_b32_e32 v114, v127
	v_mov_b32_e32 v113, v127
	v_mov_b32_e32 v112, v127
	v_mov_b32_e32 v103, v127
	v_mov_b32_e32 v102, v127
	v_mov_b32_e32 v101, v127
	v_mov_b32_e32 v100, v127
	v_mov_b32_e32 v99, v127
	v_mov_b32_e32 v98, v127
	v_mov_b32_e32 v97, v127
	v_mov_b32_e32 v96, v127
	v_mov_b32_e32 v87, v127
	v_mov_b32_e32 v86, v127
	v_mov_b32_e32 v85, v127
	v_mov_b32_e32 v84, v127
	v_mov_b32_e32 v83, v127
	v_mov_b32_e32 v82, v127
	v_mov_b32_e32 v81, v127
	v_mov_b32_e32 v80, v127
	v_mov_b32_e32 v71, v127
	v_mov_b32_e32 v70, v127
	v_mov_b32_e32 v69, v127
	v_mov_b32_e32 v68, v127
	v_mov_b32_e32 v67, v127
	v_mov_b32_e32 v66, v127
	v_mov_b32_e32 v65, v127
	v_mov_b32_e32 v64, v127
	v_mov_b32_e32 v63, v127
	v_mov_b32_e32 v62, v127
	v_mov_b32_e32 v61, v127
	v_mov_b32_e32 v60, v127
	v_mov_b32_e32 v59, v127
	v_mov_b32_e32 v58, v127
	v_mov_b32_e32 v57, v127
	v_mov_b32_e32 v56, v127
	v_mov_b32_e32 v47, v127
	v_mov_b32_e32 v46, v127
	v_mov_b32_e32 v45, v127
	v_mov_b32_e32 v44, v127
	v_mov_b32_e32 v43, v127
	v_mov_b32_e32 v42, v127
	v_mov_b32_e32 v41, v127
	v_mov_b32_e32 v40, v127
	v_mov_b32_e32 v31, v127
	v_mov_b32_e32 v30, v127
	v_mov_b32_e32 v29, v127
	v_mov_b32_e32 v28, v127
	v_mov_b32_e32 v27, v127
	v_mov_b32_e32 v26, v127
	v_mov_b32_e32 v25, v127
	v_mov_b32_e32 v24, v127
	v_mov_b32_e32 v15, v127
	v_mov_b32_e32 v14, v127
	v_mov_b32_e32 v13, v127
	v_mov_b32_e32 v12, v127
	v_mov_b32_e32 v11, v127
	v_mov_b32_e32 v10, v127
	v_mov_b32_e32 v9, v127
	v_mov_b32_e32 v8, v127
	v_mov_b32_e32 v55, v127
	v_mov_b32_e32 v54, v127
	v_mov_b32_e32 v53, v127
	v_mov_b32_e32 v52, v127
	v_mov_b32_e32 v51, v127
	v_mov_b32_e32 v50, v127
	v_mov_b32_e32 v49, v127
	v_mov_b32_e32 v48, v127
	v_mov_b32_e32 v39, v127
	v_mov_b32_e32 v38, v127
	v_mov_b32_e32 v37, v127
	v_mov_b32_e32 v36, v127
	v_mov_b32_e32 v35, v127
	v_mov_b32_e32 v34, v127
	v_mov_b32_e32 v33, v127
	v_mov_b32_e32 v32, v127
	v_mov_b32_e32 v23, v127
	v_mov_b32_e32 v22, v127
	v_mov_b32_e32 v21, v127
	v_mov_b32_e32 v20, v127
	v_mov_b32_e32 v19, v127
	v_mov_b32_e32 v18, v127
	v_mov_b32_e32 v17, v127
	v_mov_b32_e32 v16, v127
	v_mov_b32_e32 v7, v127
	v_mov_b32_e32 v6, v127
	v_mov_b32_e32 v5, v127
	v_mov_b32_e32 v4, v127
	v_mov_b32_e32 v3, v127
	v_mov_b32_e32 v2, v127
	v_mov_b32_e32 v1, v127
	v_mov_b32_e32 v0, v127
	s_cbranch_vccnz .LBB0_1390
	s_add_u32 s38, s38, 0x80
	s_addc_u32 s39, s39, 0
	s_add_u32 s59, s40, 0x100
	v_mov_b32_e32 v0, 0
	s_addc_u32 s60, s41, 0
	s_mov_b32 s40, 0
	v_mov_b32_e32 v1, v0
	v_mov_b32_e32 v2, v0
	v_mov_b32_e32 v3, v0
	v_mov_b32_e32 v4, v0
	v_mov_b32_e32 v5, v0
	v_mov_b32_e32 v6, v0
	v_mov_b32_e32 v7, v0
	v_mov_b32_e32 v16, v0
	v_mov_b32_e32 v17, v0
	v_mov_b32_e32 v18, v0
	v_mov_b32_e32 v19, v0
	v_mov_b32_e32 v20, v0
	v_mov_b32_e32 v21, v0
	v_mov_b32_e32 v22, v0
	v_mov_b32_e32 v23, v0
	v_mov_b32_e32 v32, v0
	v_mov_b32_e32 v33, v0
	v_mov_b32_e32 v34, v0
	v_mov_b32_e32 v35, v0
	v_mov_b32_e32 v36, v0
	v_mov_b32_e32 v37, v0
	v_mov_b32_e32 v38, v0
	v_mov_b32_e32 v39, v0
	v_mov_b32_e32 v48, v0
	v_mov_b32_e32 v49, v0
	v_mov_b32_e32 v50, v0
	v_mov_b32_e32 v51, v0
	v_mov_b32_e32 v52, v0
	v_mov_b32_e32 v53, v0
	v_mov_b32_e32 v54, v0
	v_mov_b32_e32 v55, v0
	v_mov_b32_e32 v8, v0
	v_mov_b32_e32 v9, v0
	v_mov_b32_e32 v10, v0
	v_mov_b32_e32 v11, v0
	v_mov_b32_e32 v12, v0
	v_mov_b32_e32 v13, v0
	v_mov_b32_e32 v14, v0
	v_mov_b32_e32 v15, v0
	v_mov_b32_e32 v24, v0
	v_mov_b32_e32 v25, v0
	v_mov_b32_e32 v26, v0
	v_mov_b32_e32 v27, v0
	v_mov_b32_e32 v28, v0
	v_mov_b32_e32 v29, v0
	v_mov_b32_e32 v30, v0
	v_mov_b32_e32 v31, v0
	v_mov_b32_e32 v40, v0
	v_mov_b32_e32 v41, v0
	v_mov_b32_e32 v42, v0
	v_mov_b32_e32 v43, v0
	v_mov_b32_e32 v44, v0
	v_mov_b32_e32 v45, v0
	v_mov_b32_e32 v46, v0
	v_mov_b32_e32 v47, v0
	v_mov_b32_e32 v56, v0
	v_mov_b32_e32 v57, v0
	v_mov_b32_e32 v58, v0
	v_mov_b32_e32 v59, v0
	v_mov_b32_e32 v60, v0
	v_mov_b32_e32 v61, v0
	v_mov_b32_e32 v62, v0
	v_mov_b32_e32 v63, v0
	v_mov_b32_e32 v64, v0
	v_mov_b32_e32 v65, v0
	v_mov_b32_e32 v66, v0
	v_mov_b32_e32 v67, v0
	v_mov_b32_e32 v68, v0
	v_mov_b32_e32 v69, v0
	v_mov_b32_e32 v70, v0
	v_mov_b32_e32 v71, v0
	v_mov_b32_e32 v80, v0
	v_mov_b32_e32 v81, v0
	v_mov_b32_e32 v82, v0
	v_mov_b32_e32 v83, v0
	v_mov_b32_e32 v84, v0
	v_mov_b32_e32 v85, v0
	v_mov_b32_e32 v86, v0
	v_mov_b32_e32 v87, v0
	v_mov_b32_e32 v96, v0
	v_mov_b32_e32 v97, v0
	v_mov_b32_e32 v98, v0
	v_mov_b32_e32 v99, v0
	v_mov_b32_e32 v100, v0
	v_mov_b32_e32 v101, v0
	v_mov_b32_e32 v102, v0
	v_mov_b32_e32 v103, v0
	v_mov_b32_e32 v112, v0
	v_mov_b32_e32 v113, v0
	v_mov_b32_e32 v114, v0
	v_mov_b32_e32 v115, v0
	v_mov_b32_e32 v116, v0
	v_mov_b32_e32 v117, v0
	v_mov_b32_e32 v118, v0
	v_mov_b32_e32 v119, v0
	v_mov_b32_e32 v72, v0
	v_mov_b32_e32 v73, v0
	v_mov_b32_e32 v74, v0
	v_mov_b32_e32 v75, v0
	v_mov_b32_e32 v76, v0
	v_mov_b32_e32 v77, v0
	v_mov_b32_e32 v78, v0
	v_mov_b32_e32 v79, v0
	v_mov_b32_e32 v88, v0
	v_mov_b32_e32 v89, v0
	v_mov_b32_e32 v90, v0
	v_mov_b32_e32 v91, v0
	v_mov_b32_e32 v92, v0
	v_mov_b32_e32 v93, v0
	v_mov_b32_e32 v94, v0
	v_mov_b32_e32 v95, v0
	v_mov_b32_e32 v104, v0
	v_mov_b32_e32 v105, v0
	v_mov_b32_e32 v106, v0
	v_mov_b32_e32 v107, v0
	v_mov_b32_e32 v108, v0
	v_mov_b32_e32 v109, v0
	v_mov_b32_e32 v110, v0
	v_mov_b32_e32 v111, v0
	v_mov_b32_e32 v120, v0
	v_mov_b32_e32 v121, v0
	v_mov_b32_e32 v122, v0
	v_mov_b32_e32 v123, v0
	v_mov_b32_e32 v124, v0
	v_mov_b32_e32 v125, v0
	v_mov_b32_e32 v126, v0
	v_mov_b32_e32 v127, v0
	.p2align 6
